# P3 SSM-final loop rewritten (packed math, prefetch depth 2, LDS D-skip), attention Q prefetch via LDS-DMA + hoisted weight loads, K/V staging rewritten with all loads in flight
# speedup vs baseline: 1.0202x; 1.0009x over previous
; __device__ __forceinline__ void attn_item(const Args& a, LAS unsigned char* lds, int item, int wave, int lane) {
;     ...
;     for (int idx = tid; idx < NKEY * 8; idx += NTHREADS) {
;         const int key = idx >> 3, ck = idx & 7; int row = -1;
;         if (key < 16) row = META_ROW + key;
;         else if (key < 32) row = -1;
;         else if (key < 160) row = blk0 > 0 ? b * SEQ + (blk0 - 1) * 128 + (key - 32) : -1;
;         else row = b * SEQ + blk0 * 128 + (key - 160);
;         u32x4 kw = (u32x4){0u, 0u, 0u, 0u}, vw = (u32x4){0u, 0u, 0u, 0u};
;         if (row >= 0) { kw = *(const u32x4*)(KB + (size_t)row * KVW + kvh * 64 + ck * 8); vw = *(const u32x4*)(VB + (size_t)row * KVW + kvh * 64 + ck * 8); }
.LBB0_248:
	s_lshl_b32 s42, s77, 7
	s_lshl_b32 s43, s84, 1
	s_ashr_i32 s66, s84, 7
	s_and_b32 s42, s42, 0x1f00
	s_and_b32 s85, s43, 62
	s_bfe_u32 s67, s84, 0x20005
	s_lshl_b32 s43, s66, 13
	s_cmp_eq_u32 s85, 0
	s_cselect_b64 s[68:69], -1, 0
	s_lshl_b32 s62, s67, 7
	v_lshl_add_u64 v[8:9], v[100:101], 0, s[62:63]
	v_lshl_add_u64 v[10:11], v[102:103], 0, s[62:63]
	s_or_b32 s62, s43, s42
	global_load_dwordx4 v[88:91], v[106:107], off
	global_load_dwordx4 v[92:95], v[106:107], off offset:16
	v_add_u32_e32 v86, v134, v96
	v_add_u32_e32 v87, v133, v96
	v_add_u32_e32 v87, 0xea00, v87
	v_cmp_lt_u32_e32 vcc, s79, v224
	v_mov_b32_e32 v98, v132
	s_and_saveexec_b64 s[74:75], vcc
	v_cmp_gt_u32_e64 s[42:43], s81, v224
	v_cmp_gt_u32_e32 vcc, s80, v224
	v_add_u32_e32 v0, s62, v132
	s_and_b64 s[42:43], s[68:69], s[42:43]
	v_add_u32_e32 v0, 0xffff7f60, v0
	s_or_b64 s[42:43], vcc, s[42:43]
	v_cndmask_b32_e64 v98, v0, -1, s[42:43]
	s_or_b64 exec, exec, s[74:75]
	v_cmp_lt_i32_e32 vcc, -1, v98
	v_mov_b32_e32 v16, 0
	v_mov_b32_e32 v17, 0
	v_mov_b32_e32 v18, 0
	v_mov_b32_e32 v19, 0
	v_mov_b32_e32 v20, 0
	v_mov_b32_e32 v21, 0
	v_mov_b32_e32 v22, 0
	v_mov_b32_e32 v23, 0
	s_and_saveexec_b64 s[42:43], vcc
	s_cbranch_execz .Lstg_skip0
	v_lshlrev_b64 v[0:1], 9, v[98:99]
	v_lshl_add_u64 v[2:3], v[10:11], 0, v[0:1]
	v_lshl_add_u64 v[0:1], v[8:9], 0, v[0:1]
	global_load_dwordx4 v[16:19], v[0:1], off
	s_nop 0
	global_load_dwordx4 v[20:23], v[2:3], off
.Lstg_skip0:
	s_or_b64 exec, exec, s[42:43]
	v_add_u32_e32 v84, 512, v224
	v_add_u32_e32 v85, 64, v132
	v_cmp_lt_u32_e32 vcc, s79, v84
	v_mov_b32_e32 v98, v85
	s_and_saveexec_b64 s[74:75], vcc
	v_cmp_gt_u32_e64 s[42:43], s81, v84
	v_cmp_gt_u32_e32 vcc, s80, v84
	v_add_u32_e32 v0, s62, v85
	s_and_b64 s[42:43], s[68:69], s[42:43]
	v_add_u32_e32 v0, 0xffff7f60, v0
	s_or_b64 s[42:43], vcc, s[42:43]
	v_cndmask_b32_e64 v98, v0, -1, s[42:43]
	s_or_b64 exec, exec, s[74:75]
	v_cmp_lt_i32_e32 vcc, -1, v98
	v_mov_b32_e32 v24, 0
	v_mov_b32_e32 v25, 0
	v_mov_b32_e32 v26, 0
	v_mov_b32_e32 v27, 0
	v_mov_b32_e32 v28, 0
	v_mov_b32_e32 v29, 0
	v_mov_b32_e32 v30, 0
	v_mov_b32_e32 v31, 0
	s_and_saveexec_b64 s[42:43], vcc
	s_cbranch_execz .Lstg_skip1
	v_lshlrev_b64 v[0:1], 9, v[98:99]
	v_lshl_add_u64 v[2:3], v[10:11], 0, v[0:1]
	v_lshl_add_u64 v[0:1], v[8:9], 0, v[0:1]
	global_load_dwordx4 v[24:27], v[0:1], off
	s_nop 0
	global_load_dwordx4 v[28:31], v[2:3], off
.Lstg_skip1:
	s_or_b64 exec, exec, s[42:43]
	v_add_u32_e32 v84, 1024, v224
	v_add_u32_e32 v85, 128, v132
	v_cmp_lt_u32_e32 vcc, s79, v84
	v_mov_b32_e32 v98, v85
	s_and_saveexec_b64 s[74:75], vcc
	v_cmp_gt_u32_e64 s[42:43], s81, v84
	v_cmp_gt_u32_e32 vcc, s80, v84
	v_add_u32_e32 v0, s62, v85
	s_and_b64 s[42:43], s[68:69], s[42:43]
	v_add_u32_e32 v0, 0xffff7f60, v0
	s_or_b64 s[42:43], vcc, s[42:43]
	v_cndmask_b32_e64 v98, v0, -1, s[42:43]
	s_or_b64 exec, exec, s[74:75]
	v_cmp_lt_i32_e32 vcc, -1, v98
	v_mov_b32_e32 v32, 0
	v_mov_b32_e32 v33, 0
	v_mov_b32_e32 v34, 0
	v_mov_b32_e32 v35, 0
	v_mov_b32_e32 v36, 0
	v_mov_b32_e32 v37, 0
	v_mov_b32_e32 v38, 0
	v_mov_b32_e32 v39, 0
	s_and_saveexec_b64 s[42:43], vcc
	s_cbranch_execz .Lstg_skip2
	v_lshlrev_b64 v[0:1], 9, v[98:99]
	v_lshl_add_u64 v[2:3], v[10:11], 0, v[0:1]
	v_lshl_add_u64 v[0:1], v[8:9], 0, v[0:1]
	global_load_dwordx4 v[32:35], v[0:1], off
	s_nop 0
	global_load_dwordx4 v[36:39], v[2:3], off
; __device__ __forceinline__ void attn_item(const Args& a, LAS unsigned char* lds, int item, int wave, int lane) {
;     ...
;     for (int idx = tid; idx < NKEY * 8; idx += NTHREADS) {
;         const int key = idx >> 3, ck = idx & 7; int row = -1;
;         if (key < 16) row = META_ROW + key;
;         else if (key < 32) row = -1;
;         else if (key < 160) row = blk0 > 0 ? b * SEQ + (blk0 - 1) * 128 + (key - 32) : -1;
;         else row = b * SEQ + blk0 * 128 + (key - 160);
;         u32x4 kw = (u32x4){0u, 0u, 0u, 0u}, vw = (u32x4){0u, 0u, 0u, 0u};
;         if (row >= 0) { kw = *(const u32x4*)(KB + (size_t)row * KVW + kvh * 64 + ck * 8); vw = *(const u32x4*)(VB + (size_t)row * KVW + kvh * 64 + ck * 8); }
.Lstg_skip2:
	s_or_b64 exec, exec, s[42:43]
	v_add_u32_e32 v84, 1536, v224
	v_add_u32_e32 v85, 192, v132
	v_cmp_lt_u32_e32 vcc, s79, v84
	v_mov_b32_e32 v98, v85
	s_and_saveexec_b64 s[74:75], vcc
	v_cmp_gt_u32_e64 s[42:43], s81, v84
	v_cmp_gt_u32_e32 vcc, s80, v84
	v_add_u32_e32 v0, s62, v85
	s_and_b64 s[42:43], s[68:69], s[42:43]
	v_add_u32_e32 v0, 0xffff7f60, v0
	s_or_b64 s[42:43], vcc, s[42:43]
	v_cndmask_b32_e64 v98, v0, -1, s[42:43]
	s_or_b64 exec, exec, s[74:75]
	v_cmp_lt_i32_e32 vcc, -1, v98
	v_mov_b32_e32 v40, 0
	v_mov_b32_e32 v41, 0
	v_mov_b32_e32 v42, 0
	v_mov_b32_e32 v43, 0
	v_mov_b32_e32 v44, 0
	v_mov_b32_e32 v45, 0
	v_mov_b32_e32 v46, 0
	v_mov_b32_e32 v47, 0
	s_and_saveexec_b64 s[42:43], vcc
	s_cbranch_execz .Lstg_skip3
	v_lshlrev_b64 v[0:1], 9, v[98:99]
	v_lshl_add_u64 v[2:3], v[10:11], 0, v[0:1]
	v_lshl_add_u64 v[0:1], v[8:9], 0, v[0:1]
	global_load_dwordx4 v[40:43], v[0:1], off
	s_nop 0
	global_load_dwordx4 v[44:47], v[2:3], off
.Lstg_skip3:
	s_or_b64 exec, exec, s[42:43]
	v_add_u32_e32 v84, 2048, v224
	v_add_u32_e32 v85, 256, v132
	v_cmp_lt_u32_e32 vcc, s79, v84
	v_mov_b32_e32 v98, v85
	s_and_saveexec_b64 s[74:75], vcc
	v_cmp_gt_u32_e64 s[42:43], s81, v84
	v_cmp_gt_u32_e32 vcc, s80, v84
	v_add_u32_e32 v0, s62, v85
	s_and_b64 s[42:43], s[68:69], s[42:43]
	v_add_u32_e32 v0, 0xffff7f60, v0
	s_or_b64 s[42:43], vcc, s[42:43]
	v_cndmask_b32_e64 v98, v0, -1, s[42:43]
	s_or_b64 exec, exec, s[74:75]
	v_cmp_lt_i32_e32 vcc, -1, v98
	v_mov_b32_e32 v48, 0
	v_mov_b32_e32 v49, 0
	v_mov_b32_e32 v50, 0
	v_mov_b32_e32 v51, 0
	v_mov_b32_e32 v52, 0
	v_mov_b32_e32 v53, 0
	v_mov_b32_e32 v54, 0
	v_mov_b32_e32 v55, 0
	s_and_saveexec_b64 s[42:43], vcc
	s_cbranch_execz .Lstg_skip4
	v_lshlrev_b64 v[0:1], 9, v[98:99]
	v_lshl_add_u64 v[2:3], v[10:11], 0, v[0:1]
	v_lshl_add_u64 v[0:1], v[8:9], 0, v[0:1]
	global_load_dwordx4 v[48:51], v[0:1], off
	s_nop 0
	global_load_dwordx4 v[52:55], v[2:3], off
.Lstg_skip4:
	s_or_b64 exec, exec, s[42:43]
	v_add_u32_e32 v84, 2560, v224
	v_add_u32_e32 v85, 320, v132
	v_cmp_lt_u32_e32 vcc, s79, v84
	v_mov_b32_e32 v98, v85
	s_and_saveexec_b64 s[74:75], vcc
	v_cmp_gt_u32_e64 s[42:43], s81, v84
	v_cmp_gt_u32_e32 vcc, s80, v84
	v_add_u32_e32 v0, s62, v85
	s_and_b64 s[42:43], s[68:69], s[42:43]
	v_add_u32_e32 v0, 0xffff7f60, v0
	s_or_b64 s[42:43], vcc, s[42:43]
	v_cndmask_b32_e64 v98, v0, -1, s[42:43]
	s_or_b64 exec, exec, s[74:75]
	v_cmp_lt_i32_e32 vcc, -1, v98
	v_mov_b32_e32 v56, 0
	v_mov_b32_e32 v57, 0
	v_mov_b32_e32 v58, 0
	v_mov_b32_e32 v59, 0
	v_mov_b32_e32 v60, 0
	v_mov_b32_e32 v61, 0
	v_mov_b32_e32 v62, 0
	v_mov_b32_e32 v63, 0
	s_and_saveexec_b64 s[42:43], vcc
	s_cbranch_execz .Lstg_skip5
	v_lshlrev_b64 v[0:1], 9, v[98:99]
	v_lshl_add_u64 v[2:3], v[10:11], 0, v[0:1]
	v_lshl_add_u64 v[0:1], v[8:9], 0, v[0:1]
	global_load_dwordx4 v[56:59], v[0:1], off
	s_nop 0
	global_load_dwordx4 v[60:63], v[2:3], off
.Lstg_skip5:
	s_or_b64 exec, exec, s[42:43]
	s_cmp_lt_u32 s33, 4
	s_cbranch_scc0 .Lstg_no6a
	v_add_u32_e32 v84, 3072, v224
	v_add_u32_e32 v85, 384, v132
	v_cmp_lt_u32_e32 vcc, s79, v84
	v_mov_b32_e32 v98, v85
	s_and_saveexec_b64 s[74:75], vcc
	v_cmp_gt_u32_e64 s[42:43], s81, v84
	v_cmp_gt_u32_e32 vcc, s80, v84
	v_add_u32_e32 v0, s62, v85
	s_and_b64 s[42:43], s[68:69], s[42:43]
	v_add_u32_e32 v0, 0xffff7f60, v0
	s_or_b64 s[42:43], vcc, s[42:43]
	v_cndmask_b32_e64 v98, v0, -1, s[42:43]
	s_or_b64 exec, exec, s[74:75]
	v_cmp_lt_i32_e32 vcc, -1, v98
	v_mov_b32_e32 v64, 0
	v_mov_b32_e32 v65, 0
	v_mov_b32_e32 v66, 0
	v_mov_b32_e32 v67, 0
	v_mov_b32_e32 v68, 0
	v_mov_b32_e32 v69, 0
	v_mov_b32_e32 v70, 0
	v_mov_b32_e32 v71, 0
	s_and_saveexec_b64 s[42:43], vcc
	s_cbranch_execz .Lstg_skip6
	v_lshlrev_b64 v[0:1], 9, v[98:99]
	v_lshl_add_u64 v[2:3], v[10:11], 0, v[0:1]
	v_lshl_add_u64 v[0:1], v[8:9], 0, v[0:1]
	global_load_dwordx4 v[64:67], v[0:1], off
	s_nop 0
	global_load_dwordx4 v[68:71], v[2:3], off

; #define LAS __attribute__((address_space(3)))
; __device__ __forceinline__ unsigned cvt_pk(float lo, float hi) { unsigned r; asm volatile("v_cvt_pk_bf16_f32 %0, %1, %2" : "=v"(r) : "v"(lo), "v"(hi)); return r; }
; __device__ __forceinline__ float bf_lo(unsigned w) { return __uint_as_float(w << 16); }
; __device__ __forceinline__ float bf_hi(unsigned w) { return __uint_as_float(w & 0xffff0000u); }
; __device__ __forceinline__ void attn_item(const Args& a, LAS unsigned char* lds, int item, int wave, int lane) {
;     ...
;         float kf[8] = {bf_lo(kw.x), bf_hi(kw.x), bf_lo(kw.y), bf_hi(kw.y), bf_lo(kw.z), bf_hi(kw.z), bf_lo(kw.w), bf_hi(kw.w)};
;         float ss = 0.f;
; #pragma unroll
;         for (int e = 0; e < 8; ++e) ss += kf[e] * kf[e];
;         ss += __shfl_xor(ss, 1); ss += __shfl_xor(ss, 2); ss += __shfl_xor(ss, 4);
;         const float rs = __builtin_amdgcn_rsqf(ss * (1.0f / 64.0f) + EPS);
;         const f32x4 g0 = *(const f32x4*)(knw + ck * 8), g1 = *(const f32x4*)(knw + ck * 8 + 4);
;         u32x4 o; o.x = cvt_pk(kf[0] * rs * g0.x, kf[1] * rs * g0.y); o.y = cvt_pk(kf[2] * rs * g0.z, kf[3] * rs * g0.w);
;         o.z = cvt_pk(kf[4] * rs * g1.x, kf[5] * rs * g1.y); o.w = cvt_pk(kf[6] * rs * g1.z, kf[7] * rs * g1.w);
;         *(LAS u32x4*)(lds + ATT_K_OFF + key * KP + ck * 16) = o;
;         LAS unsigned short* vt = (LAS unsigned short*)(lds + ATT_V_OFF + (ck * 8) * VP + key * 2);
;         const unsigned vv[4] = {vw.x, vw.y, vw.z, vw.w};
; #pragma unroll
;         for (int e = 0; e < 4; ++e) { vt[(2 * e) * (VP / 2)] = (unsigned short)(vv[e] & 0xffffu); vt[(2 * e + 1) * (VP / 2)] = (unsigned short)(vv[e] >> 16); }
.Lstg_no6a:
	s_waitcnt vmcnt(0)
	v_lshlrev_b32_e32 v0, 16, v16
	v_and_b32_e32 v1, 0xffff0000, v16
	v_lshlrev_b32_e32 v2, 16, v17
	v_and_b32_e32 v3, 0xffff0000, v17
	v_lshlrev_b32_e32 v4, 16, v18
	v_and_b32_e32 v5, 0xffff0000, v18
	v_lshlrev_b32_e32 v6, 16, v19
	v_and_b32_e32 v7, 0xffff0000, v19
	v_pk_mul_f32 v[0:1], v[0:1], v[0:1]
	v_pk_mul_f32 v[2:3], v[2:3], v[2:3]
	v_pk_fma_f32 v[0:1], v[4:5], v[4:5], v[0:1]
	v_pk_fma_f32 v[2:3], v[6:7], v[6:7], v[2:3]
	s_nop 0
	v_pk_add_f32 v[0:1], v[0:1], v[2:3]
	s_nop 0
	v_add_f32_e32 v72, v0, v1
	v_lshlrev_b32_e32 v0, 16, v24
	v_and_b32_e32 v1, 0xffff0000, v24
	v_lshlrev_b32_e32 v2, 16, v25
	v_and_b32_e32 v3, 0xffff0000, v25
	v_lshlrev_b32_e32 v4, 16, v26
	v_and_b32_e32 v5, 0xffff0000, v26
	v_lshlrev_b32_e32 v6, 16, v27
	v_and_b32_e32 v7, 0xffff0000, v27
	v_pk_mul_f32 v[0:1], v[0:1], v[0:1]
	v_pk_mul_f32 v[2:3], v[2:3], v[2:3]
	v_pk_fma_f32 v[0:1], v[4:5], v[4:5], v[0:1]
	v_pk_fma_f32 v[2:3], v[6:7], v[6:7], v[2:3]
	s_nop 0
	v_pk_add_f32 v[0:1], v[0:1], v[2:3]
	s_nop 0
	v_add_f32_e32 v73, v0, v1
	v_lshlrev_b32_e32 v0, 16, v32
	v_and_b32_e32 v1, 0xffff0000, v32
	v_lshlrev_b32_e32 v2, 16, v33
	v_and_b32_e32 v3, 0xffff0000, v33
	v_lshlrev_b32_e32 v4, 16, v34
	v_and_b32_e32 v5, 0xffff0000, v34
	v_lshlrev_b32_e32 v6, 16, v35
	v_and_b32_e32 v7, 0xffff0000, v35
	v_pk_mul_f32 v[0:1], v[0:1], v[0:1]
	v_pk_mul_f32 v[2:3], v[2:3], v[2:3]
	v_pk_fma_f32 v[0:1], v[4:5], v[4:5], v[0:1]
	v_pk_fma_f32 v[2:3], v[6:7], v[6:7], v[2:3]
	s_nop 0
	v_pk_add_f32 v[0:1], v[0:1], v[2:3]
	s_nop 0
	v_add_f32_e32 v74, v0, v1
	v_lshlrev_b32_e32 v0, 16, v40
	v_and_b32_e32 v1, 0xffff0000, v40
	v_lshlrev_b32_e32 v2, 16, v41
	v_and_b32_e32 v3, 0xffff0000, v41
	v_lshlrev_b32_e32 v4, 16, v42
	v_and_b32_e32 v5, 0xffff0000, v42
	v_lshlrev_b32_e32 v6, 16, v43
	v_and_b32_e32 v7, 0xffff0000, v43
	v_pk_mul_f32 v[0:1], v[0:1], v[0:1]
	v_pk_mul_f32 v[2:3], v[2:3], v[2:3]
	v_pk_fma_f32 v[0:1], v[4:5], v[4:5], v[0:1]
	v_pk_fma_f32 v[2:3], v[6:7], v[6:7], v[2:3]
	s_nop 0
	v_pk_add_f32 v[0:1], v[0:1], v[2:3]
	s_nop 0
	v_add_f32_e32 v75, v0, v1
	v_lshlrev_b32_e32 v0, 16, v48
	v_and_b32_e32 v1, 0xffff0000, v48
	v_lshlrev_b32_e32 v2, 16, v49
	v_and_b32_e32 v3, 0xffff0000, v49
	v_lshlrev_b32_e32 v4, 16, v50
	v_and_b32_e32 v5, 0xffff0000, v50
	v_lshlrev_b32_e32 v6, 16, v51
	v_and_b32_e32 v7, 0xffff0000, v51
	v_pk_mul_f32 v[0:1], v[0:1], v[0:1]
	v_pk_mul_f32 v[2:3], v[2:3], v[2:3]
	v_pk_fma_f32 v[0:1], v[4:5], v[4:5], v[0:1]
	v_pk_fma_f32 v[2:3], v[6:7], v[6:7], v[2:3]
	s_nop 0
	v_pk_add_f32 v[0:1], v[0:1], v[2:3]
	s_nop 0
	v_add_f32_e32 v76, v0, v1
	v_lshlrev_b32_e32 v0, 16, v56
	v_and_b32_e32 v1, 0xffff0000, v56
	v_lshlrev_b32_e32 v2, 16, v57
	v_and_b32_e32 v3, 0xffff0000, v57
	v_lshlrev_b32_e32 v4, 16, v58
	v_and_b32_e32 v5, 0xffff0000, v58
	v_lshlrev_b32_e32 v6, 16, v59
	v_and_b32_e32 v7, 0xffff0000, v59
	v_pk_mul_f32 v[0:1], v[0:1], v[0:1]
	v_pk_mul_f32 v[2:3], v[2:3], v[2:3]
	v_pk_fma_f32 v[0:1], v[4:5], v[4:5], v[0:1]
	v_pk_fma_f32 v[2:3], v[6:7], v[6:7], v[2:3]
	s_nop 0
	v_pk_add_f32 v[0:1], v[0:1], v[2:3]
	s_nop 0
	v_add_f32_e32 v77, v0, v1
	ds_bpermute_b32 v80, v113, v72
	ds_bpermute_b32 v81, v113, v73
	ds_bpermute_b32 v82, v113, v74
	ds_bpermute_b32 v83, v113, v75
	ds_bpermute_b32 v84, v113, v76
	ds_bpermute_b32 v85, v113, v77
	s_waitcnt lgkmcnt(0)
	v_add_f32_e32 v72, v72, v80
	v_add_f32_e32 v73, v73, v81
	v_add_f32_e32 v74, v74, v82
	v_add_f32_e32 v75, v75, v83
	v_add_f32_e32 v76, v76, v84
	v_add_f32_e32 v77, v77, v85
	ds_bpermute_b32 v80, v124, v72
	ds_bpermute_b32 v81, v124, v73
	ds_bpermute_b32 v82, v124, v74
	ds_bpermute_b32 v83, v124, v75
	ds_bpermute_b32 v84, v124, v76
	ds_bpermute_b32 v85, v124, v77
	s_waitcnt lgkmcnt(0)
	v_add_f32_e32 v72, v72, v80
	v_add_f32_e32 v73, v73, v81
	v_add_f32_e32 v74, v74, v82
	v_add_f32_e32 v75, v75, v83
	v_add_f32_e32 v76, v76, v84
	v_add_f32_e32 v77, v77, v85
	ds_bpermute_b32 v80, v125, v72
	ds_bpermute_b32 v81, v125, v73
	ds_bpermute_b32 v82, v125, v74
	ds_bpermute_b32 v83, v125, v75
	ds_bpermute_b32 v84, v125, v76
	ds_bpermute_b32 v85, v125, v77
	s_waitcnt lgkmcnt(0)
	v_add_f32_e32 v72, v72, v80
	v_add_f32_e32 v73, v73, v81
	v_add_f32_e32 v74, v74, v82
	v_add_f32_e32 v75, v75, v83
	v_add_f32_e32 v76, v76, v84
	v_add_f32_e32 v77, v77, v85
	v_fmamk_f32 v12, v72, 0x3c800000, v135
	v_rsq_f32_e32 v12, v12
	v_lshlrev_b32_e32 v0, 16, v16
	v_and_b32_e32 v1, 0xffff0000, v16
	v_lshlrev_b32_e32 v2, 16, v17
	v_and_b32_e32 v3, 0xffff0000, v17
	v_lshlrev_b32_e32 v4, 16, v18
	v_and_b32_e32 v5, 0xffff0000, v18
	v_lshlrev_b32_e32 v6, 16, v19
	v_and_b32_e32 v7, 0xffff0000, v19
	v_pk_mul_f32 v[0:1], v[0:1], v[12:13] op_sel_hi:[1,0]
	v_pk_mul_f32 v[2:3], v[2:3], v[12:13] op_sel_hi:[1,0]
	v_pk_mul_f32 v[4:5], v[4:5], v[12:13] op_sel_hi:[1,0]
	v_pk_mul_f32 v[6:7], v[6:7], v[12:13] op_sel_hi:[1,0]
	v_pk_mul_f32 v[0:1], v[0:1], v[88:89]
	v_pk_mul_f32 v[2:3], v[2:3], v[90:91]
	v_pk_mul_f32 v[4:5], v[4:5], v[92:93]
	v_pk_mul_f32 v[6:7], v[6:7], v[94:95]
	s_nop 0
	v_cvt_pk_bf16_f32 v12, v0, v1
	v_cvt_pk_bf16_f32 v13, v2, v3
	v_cvt_pk_bf16_f32 v14, v4, v5
	v_cvt_pk_bf16_f32 v15, v6, v7
	ds_write_b128 v86, v[12:15]
	ds_write_b16 v87, v20
	ds_write_b16_d16_hi v87, v20 offset:840
	ds_write_b16 v87, v21 offset:1680
	ds_write_b16_d16_hi v87, v21 offset:2520
	ds_write_b16 v87, v22 offset:3360
	ds_write_b16_d16_hi v87, v22 offset:4200
	ds_write_b16 v87, v23 offset:5040
	ds_write_b16_d16_hi v87, v23 offset:5880
	v_fmamk_f32 v12, v73, 0x3c800000, v135
	v_rsq_f32_e32 v12, v12
	v_lshlrev_b32_e32 v0, 16, v24
	v_and_b32_e32 v1, 0xffff0000, v24
	v_lshlrev_b32_e32 v2, 16, v25
	v_and_b32_e32 v3, 0xffff0000, v25
	v_lshlrev_b32_e32 v4, 16, v26
; #define LAS __attribute__((address_space(3)))
; __device__ __forceinline__ unsigned cvt_pk(float lo, float hi) { unsigned r; asm volatile("v_cvt_pk_bf16_f32 %0, %1, %2" : "=v"(r) : "v"(lo), "v"(hi)); return r; }
; __device__ __forceinline__ void attn_item(const Args& a, LAS unsigned char* lds, int item, int wave, int lane) {
;     ...
;         const float rs = __builtin_amdgcn_rsqf(ss * (1.0f / 64.0f) + EPS);
;         const f32x4 g0 = *(const f32x4*)(knw + ck * 8), g1 = *(const f32x4*)(knw + ck * 8 + 4);
;         u32x4 o; o.x = cvt_pk(kf[0] * rs * g0.x, kf[1] * rs * g0.y); o.y = cvt_pk(kf[2] * rs * g0.z, kf[3] * rs * g0.w);
;         o.z = cvt_pk(kf[4] * rs * g1.x, kf[5] * rs * g1.y); o.w = cvt_pk(kf[6] * rs * g1.z, kf[7] * rs * g1.w);
;         *(LAS u32x4*)(lds + ATT_K_OFF + key * KP + ck * 16) = o;
;         LAS unsigned short* vt = (LAS unsigned short*)(lds + ATT_V_OFF + (ck * 8) * VP + key * 2);
;         const unsigned vv[4] = {vw.x, vw.y, vw.z, vw.w};
; #pragma unroll
;         for (int e = 0; e < 4; ++e) { vt[(2 * e) * (VP / 2)] = (unsigned short)(vv[e] & 0xffffu); vt[(2 * e + 1) * (VP / 2)] = (unsigned short)(vv[e] >> 16); }
	v_and_b32_e32 v5, 0xffff0000, v26
	v_lshlrev_b32_e32 v6, 16, v27
	v_and_b32_e32 v7, 0xffff0000, v27
	v_pk_mul_f32 v[0:1], v[0:1], v[12:13] op_sel_hi:[1,0]
	v_pk_mul_f32 v[2:3], v[2:3], v[12:13] op_sel_hi:[1,0]
	v_pk_mul_f32 v[4:5], v[4:5], v[12:13] op_sel_hi:[1,0]
	v_pk_mul_f32 v[6:7], v[6:7], v[12:13] op_sel_hi:[1,0]
	v_pk_mul_f32 v[0:1], v[0:1], v[88:89]
	v_pk_mul_f32 v[2:3], v[2:3], v[90:91]
	v_pk_mul_f32 v[4:5], v[4:5], v[92:93]
	v_pk_mul_f32 v[6:7], v[6:7], v[94:95]
	s_nop 0
	v_cvt_pk_bf16_f32 v12, v0, v1
	v_cvt_pk_bf16_f32 v13, v2, v3
	v_cvt_pk_bf16_f32 v14, v4, v5
	v_cvt_pk_bf16_f32 v15, v6, v7
	ds_write_b128 v86, v[12:15] offset:9216
	ds_write_b16 v87, v28 offset:128
	ds_write_b16_d16_hi v87, v28 offset:968
	ds_write_b16 v87, v29 offset:1808
	ds_write_b16_d16_hi v87, v29 offset:2648
	ds_write_b16 v87, v30 offset:3488
	ds_write_b16_d16_hi v87, v30 offset:4328
	ds_write_b16 v87, v31 offset:5168
	ds_write_b16_d16_hi v87, v31 offset:6008
	v_fmamk_f32 v12, v74, 0x3c800000, v135
	v_rsq_f32_e32 v12, v12
	v_lshlrev_b32_e32 v0, 16, v32
	v_and_b32_e32 v1, 0xffff0000, v32
	v_lshlrev_b32_e32 v2, 16, v33
	v_and_b32_e32 v3, 0xffff0000, v33
	v_lshlrev_b32_e32 v4, 16, v34
	v_and_b32_e32 v5, 0xffff0000, v34
	v_lshlrev_b32_e32 v6, 16, v35
	v_and_b32_e32 v7, 0xffff0000, v35
	v_pk_mul_f32 v[0:1], v[0:1], v[12:13] op_sel_hi:[1,0]
	v_pk_mul_f32 v[2:3], v[2:3], v[12:13] op_sel_hi:[1,0]
	v_pk_mul_f32 v[4:5], v[4:5], v[12:13] op_sel_hi:[1,0]
	v_pk_mul_f32 v[6:7], v[6:7], v[12:13] op_sel_hi:[1,0]
	v_pk_mul_f32 v[0:1], v[0:1], v[88:89]
	v_pk_mul_f32 v[2:3], v[2:3], v[90:91]
	v_pk_mul_f32 v[4:5], v[4:5], v[92:93]
	v_pk_mul_f32 v[6:7], v[6:7], v[94:95]
	s_nop 0
	v_cvt_pk_bf16_f32 v12, v0, v1
	v_cvt_pk_bf16_f32 v13, v2, v3
	v_cvt_pk_bf16_f32 v14, v4, v5
	v_cvt_pk_bf16_f32 v15, v6, v7
	ds_write_b128 v86, v[12:15] offset:18432
	ds_write_b16 v87, v36 offset:256
	ds_write_b16_d16_hi v87, v36 offset:1096
	ds_write_b16 v87, v37 offset:1936
	ds_write_b16_d16_hi v87, v37 offset:2776
	ds_write_b16 v87, v38 offset:3616
	ds_write_b16_d16_hi v87, v38 offset:4456
	ds_write_b16 v87, v39 offset:5296
	ds_write_b16_d16_hi v87, v39 offset:6136
	v_fmamk_f32 v12, v75, 0x3c800000, v135
	v_rsq_f32_e32 v12, v12
	v_lshlrev_b32_e32 v0, 16, v40
	v_and_b32_e32 v1, 0xffff0000, v40
	v_lshlrev_b32_e32 v2, 16, v41
	v_and_b32_e32 v3, 0xffff0000, v41
	v_lshlrev_b32_e32 v4, 16, v42
	v_and_b32_e32 v5, 0xffff0000, v42
	v_lshlrev_b32_e32 v6, 16, v43
	v_and_b32_e32 v7, 0xffff0000, v43
	v_pk_mul_f32 v[0:1], v[0:1], v[12:13] op_sel_hi:[1,0]
	v_pk_mul_f32 v[2:3], v[2:3], v[12:13] op_sel_hi:[1,0]
	v_pk_mul_f32 v[4:5], v[4:5], v[12:13] op_sel_hi:[1,0]
	v_pk_mul_f32 v[6:7], v[6:7], v[12:13] op_sel_hi:[1,0]
	v_pk_mul_f32 v[0:1], v[0:1], v[88:89]
	v_pk_mul_f32 v[2:3], v[2:3], v[90:91]
	v_pk_mul_f32 v[4:5], v[4:5], v[92:93]
	v_pk_mul_f32 v[6:7], v[6:7], v[94:95]
	s_nop 0
	v_cvt_pk_bf16_f32 v12, v0, v1
	v_cvt_pk_bf16_f32 v13, v2, v3
	v_cvt_pk_bf16_f32 v14, v4, v5
	v_cvt_pk_bf16_f32 v15, v6, v7
	ds_write_b128 v86, v[12:15] offset:27648
	ds_write_b16 v87, v44 offset:384
	ds_write_b16_d16_hi v87, v44 offset:1224
	ds_write_b16 v87, v45 offset:2064
	ds_write_b16_d16_hi v87, v45 offset:2904
	ds_write_b16 v87, v46 offset:3744
	ds_write_b16_d16_hi v87, v46 offset:4584
	ds_write_b16 v87, v47 offset:5424
	ds_write_b16_d16_hi v87, v47 offset:6264
	v_fmamk_f32 v12, v76, 0x3c800000, v135
	v_rsq_f32_e32 v12, v12
	v_lshlrev_b32_e32 v0, 16, v48
	v_and_b32_e32 v1, 0xffff0000, v48
	v_lshlrev_b32_e32 v2, 16, v49
	v_and_b32_e32 v3, 0xffff0000, v49
	v_lshlrev_b32_e32 v4, 16, v50
	v_and_b32_e32 v5, 0xffff0000, v50
	v_lshlrev_b32_e32 v6, 16, v51
	v_and_b32_e32 v7, 0xffff0000, v51
	v_pk_mul_f32 v[0:1], v[0:1], v[12:13] op_sel_hi:[1,0]
	v_pk_mul_f32 v[2:3], v[2:3], v[12:13] op_sel_hi:[1,0]
	v_pk_mul_f32 v[4:5], v[4:5], v[12:13] op_sel_hi:[1,0]
	v_pk_mul_f32 v[6:7], v[6:7], v[12:13] op_sel_hi:[1,0]
	v_pk_mul_f32 v[0:1], v[0:1], v[88:89]
	v_pk_mul_f32 v[2:3], v[2:3], v[90:91]
	v_pk_mul_f32 v[4:5], v[4:5], v[92:93]
	v_pk_mul_f32 v[6:7], v[6:7], v[94:95]
	s_nop 0
	v_cvt_pk_bf16_f32 v12, v0, v1
	v_cvt_pk_bf16_f32 v13, v2, v3
	v_cvt_pk_bf16_f32 v14, v4, v5
	v_cvt_pk_bf16_f32 v15, v6, v7
	ds_write_b128 v86, v[12:15] offset:36864
	ds_write_b16 v87, v52 offset:512
	ds_write_b16_d16_hi v87, v52 offset:1352
	ds_write_b16 v87, v53 offset:2192
	ds_write_b16_d16_hi v87, v53 offset:3032
	ds_write_b16 v87, v54 offset:3872
	ds_write_b16_d16_hi v87, v54 offset:4712
	ds_write_b16 v87, v55 offset:5552
	ds_write_b16_d16_hi v87, v55 offset:6392
	v_fmamk_f32 v12, v77, 0x3c800000, v135
	v_rsq_f32_e32 v12, v12
	v_lshlrev_b32_e32 v0, 16, v56
	v_and_b32_e32 v1, 0xffff0000, v56
	v_lshlrev_b32_e32 v2, 16, v57
	v_and_b32_e32 v3, 0xffff0000, v57
	v_lshlrev_b32_e32 v4, 16, v58
	v_and_b32_e32 v5, 0xffff0000, v58
	v_lshlrev_b32_e32 v6, 16, v59
	v_and_b32_e32 v7, 0xffff0000, v59
	v_pk_mul_f32 v[0:1], v[0:1], v[12:13] op_sel_hi:[1,0]
	v_pk_mul_f32 v[2:3], v[2:3], v[12:13] op_sel_hi:[1,0]
	v_pk_mul_f32 v[4:5], v[4:5], v[12:13] op_sel_hi:[1,0]
	v_pk_mul_f32 v[6:7], v[6:7], v[12:13] op_sel_hi:[1,0]
	v_pk_mul_f32 v[0:1], v[0:1], v[88:89]
	v_pk_mul_f32 v[2:3], v[2:3], v[90:91]
	v_pk_mul_f32 v[4:5], v[4:5], v[92:93]
	v_pk_mul_f32 v[6:7], v[6:7], v[94:95]
	s_nop 0
	v_cvt_pk_bf16_f32 v12, v0, v1
	v_cvt_pk_bf16_f32 v13, v2, v3
	v_cvt_pk_bf16_f32 v14, v4, v5
	v_cvt_pk_bf16_f32 v15, v6, v7
	ds_write_b128 v86, v[12:15] offset:46080
	ds_write_b16 v87, v60 offset:640
	ds_write_b16_d16_hi v87, v60 offset:1480
	ds_write_b16 v87, v61 offset:2320
	ds_write_b16_d16_hi v87, v61 offset:3160
	ds_write_b16 v87, v62 offset:4000
	ds_write_b16_d16_hi v87, v62 offset:4840
	ds_write_b16 v87, v63 offset:5680
	ds_write_b16_d16_hi v87, v63 offset:6520
	s_cmp_lt_u32 s33, 4
	s_cbranch_scc0 .Lstg_no6b
; #define LAS __attribute__((address_space(3)))
; __device__ __forceinline__ unsigned cvt_pk(float lo, float hi) { unsigned r; asm volatile("v_cvt_pk_bf16_f32 %0, %1, %2" : "=v"(r) : "v"(lo), "v"(hi)); return r; }
; __device__ __forceinline__ float bf_lo(unsigned w) { return __uint_as_float(w << 16); }
; __device__ __forceinline__ float bf_hi(unsigned w) { return __uint_as_float(w & 0xffff0000u); }
; __device__ __forceinline__ void attn_item(const Args& a, LAS unsigned char* lds, int item, int wave, int lane) {
;     ...
;         float kf[8] = {bf_lo(kw.x), bf_hi(kw.x), bf_lo(kw.y), bf_hi(kw.y), bf_lo(kw.z), bf_hi(kw.z), bf_lo(kw.w), bf_hi(kw.w)};
;         float ss = 0.f;
; #pragma unroll
;         for (int e = 0; e < 8; ++e) ss += kf[e] * kf[e];
;         ss += __shfl_xor(ss, 1); ss += __shfl_xor(ss, 2); ss += __shfl_xor(ss, 4);
;         const float rs = __builtin_amdgcn_rsqf(ss * (1.0f / 64.0f) + EPS);
;         const f32x4 g0 = *(const f32x4*)(knw + ck * 8), g1 = *(const f32x4*)(knw + ck * 8 + 4);
;         u32x4 o; o.x = cvt_pk(kf[0] * rs * g0.x, kf[1] * rs * g0.y); o.y = cvt_pk(kf[2] * rs * g0.z, kf[3] * rs * g0.w);
;         o.z = cvt_pk(kf[4] * rs * g1.x, kf[5] * rs * g1.y); o.w = cvt_pk(kf[6] * rs * g1.z, kf[7] * rs * g1.w);
;         *(LAS u32x4*)(lds + ATT_K_OFF + key * KP + ck * 16) = o;
;         LAS unsigned short* vt = (LAS unsigned short*)(lds + ATT_V_OFF + (ck * 8) * VP + key * 2);
;         const unsigned vv[4] = {vw.x, vw.y, vw.z, vw.w};
; #pragma unroll
;         for (int e = 0; e < 4; ++e) { vt[(2 * e) * (VP / 2)] = (unsigned short)(vv[e] & 0xffffu); vt[(2 * e + 1) * (VP / 2)] = (unsigned short)(vv[e] >> 16); }
;     }
;     __syncthreads();
;     const int r = wave >> 1, qh = wave & 1, hq = kvh * 4 + r, ql = lane & 31, hi = lane >> 5;
;     const float sink = a.in[6][hq];
;     const float* qnw = a.in[4];
;     const float L2E = 1.4426950408889634f;
;     for (int q4 = 0; q4 < 4; ++q4) {
;         const int bl = q4 >> 1, qb = q4 & 1, blk = blk0 + bl;
;         const int qblk = 2 * qh + qb;
;         const size_t qrow = (size_t)b * SEQ + blk * 128 + qblk * 32 + ql;
;         bf16x8 qf[4];
;         {
;             u32x4 qw[4]; float ss = 0.f;
; #pragma unroll
;             for (int ks = 0; ks < 4; ++ks) { qw[ks] = *(const u32x4*)(QB + qrow * DM + hq * 64 + 16 * ks + 8 * hi);
	v_lshlrev_b32_e32 v0, 16, v64
	v_and_b32_e32 v1, 0xffff0000, v64
	v_lshlrev_b32_e32 v2, 16, v65
	v_and_b32_e32 v3, 0xffff0000, v65
	v_lshlrev_b32_e32 v4, 16, v66
	v_and_b32_e32 v5, 0xffff0000, v66
	v_lshlrev_b32_e32 v6, 16, v67
	v_and_b32_e32 v7, 0xffff0000, v67
	v_pk_mul_f32 v[0:1], v[0:1], v[0:1]
	v_pk_mul_f32 v[2:3], v[2:3], v[2:3]
	v_pk_fma_f32 v[0:1], v[4:5], v[4:5], v[0:1]
	v_pk_fma_f32 v[2:3], v[6:7], v[6:7], v[2:3]
	s_nop 0
	v_pk_add_f32 v[0:1], v[0:1], v[2:3]
	s_nop 0
	v_add_f32_e32 v78, v0, v1
	ds_bpermute_b32 v80, v113, v78
	s_waitcnt lgkmcnt(0)
	v_add_f32_e32 v78, v78, v80
	ds_bpermute_b32 v80, v124, v78
	s_waitcnt lgkmcnt(0)
	v_add_f32_e32 v78, v78, v80
	ds_bpermute_b32 v80, v125, v78
	s_waitcnt lgkmcnt(0)
	v_add_f32_e32 v78, v78, v80
	v_fmamk_f32 v12, v78, 0x3c800000, v135
	v_rsq_f32_e32 v12, v12
	v_lshlrev_b32_e32 v0, 16, v64
	v_and_b32_e32 v1, 0xffff0000, v64
	v_lshlrev_b32_e32 v2, 16, v65
	v_and_b32_e32 v3, 0xffff0000, v65
	v_lshlrev_b32_e32 v4, 16, v66
	v_and_b32_e32 v5, 0xffff0000, v66
	v_lshlrev_b32_e32 v6, 16, v67
	v_and_b32_e32 v7, 0xffff0000, v67
	v_pk_mul_f32 v[0:1], v[0:1], v[12:13] op_sel_hi:[1,0]
	v_pk_mul_f32 v[2:3], v[2:3], v[12:13] op_sel_hi:[1,0]
	v_pk_mul_f32 v[4:5], v[4:5], v[12:13] op_sel_hi:[1,0]
	v_pk_mul_f32 v[6:7], v[6:7], v[12:13] op_sel_hi:[1,0]
	v_pk_mul_f32 v[0:1], v[0:1], v[88:89]
	v_pk_mul_f32 v[2:3], v[2:3], v[90:91]
	v_pk_mul_f32 v[4:5], v[4:5], v[92:93]
	v_pk_mul_f32 v[6:7], v[6:7], v[94:95]
	s_nop 0
	v_cvt_pk_bf16_f32 v12, v0, v1
	v_cvt_pk_bf16_f32 v13, v2, v3
	v_cvt_pk_bf16_f32 v14, v4, v5
	v_cvt_pk_bf16_f32 v15, v6, v7
	ds_write_b128 v86, v[12:15] offset:55296
	ds_write_b16 v87, v68 offset:768
	ds_write_b16_d16_hi v87, v68 offset:1608
	ds_write_b16 v87, v69 offset:2448
	ds_write_b16_d16_hi v87, v69 offset:3288
	ds_write_b16 v87, v70 offset:4128
	ds_write_b16_d16_hi v87, v70 offset:4968
	ds_write_b16 v87, v71 offset:5808
	ds_write_b16_d16_hi v87, v71 offset:6648
.Lstg_no6b:
	s_lshl_b32 s42, s67, 2
	s_add_i32 s62, s42, s41
	s_lshl_b32 s42, s62, 2
	v_mov_b32_e32 v0, s42
	s_waitcnt lgkmcnt(0)
	s_barrier
	global_load_dword v98, v0, s[88:89]
	s_ashr_i32 s67, s66, 31
	s_lshl_b32 s62, s62, 7
	s_lshl_b64 s[42:43], s[66:67], 13
	v_lshl_add_u64 v[116:117], v[108:109], 0, s[62:63]
	v_lshl_add_u64 v[118:119], v[114:115], 0, s[62:63]
	s_lshl_b32 s100, s33, 12
	s_add_i32 s100, s100, 113664
	v_lshl_add_u32 v238, v128, 4, s100
	s_lshl_b32 s98, s85, 7
	s_add_i32 s98, s98, s42
	s_lshl_b32 s99, s65, 5
	s_or_b32 s98, s98, s99
	v_or_b32_e32 v222, s98, v130
	v_lshlrev_b32_e32 v222, 11, v222
	v_mov_b32_e32 v223, 0
	v_lshl_add_u64 v[220:221], v[116:117], 0, v[222:223]
	s_add_i32 m0, s100, 0
	s_nop 0
	global_load_lds_dwordx4 v[220:221], off
	s_add_i32 m0, s100, 992
	s_nop 0
	global_load_lds_dwordx4 v[220:221], off offset:32
	s_add_i32 m0, s100, 1984
	s_nop 0
	global_load_lds_dwordx4 v[220:221], off offset:64
	s_add_i32 m0, s100, 2976
	s_nop 0
	global_load_lds_dwordx4 v[220:221], off offset:96
	s_mov_b32 s62, 0
	s_waitcnt vmcnt(0)
	v_mul_f32_e32 v138, 0x3fb8aa3b, v98
	s_branch .LBB0_256
